# S5 pass-1 phase rewritten by hand: 32x32x16 f16 MFMA gives B*u with component on lane, scan runs from accumulators via DPP, no LDS transpose
# speedup vs baseline: 1.0134x; 1.0134x over previous
.LBB0_526:
	s_cmp_lt_i32 s90, 7
	s_cselect_b64 s[0:1], -1, 0
	s_and_b64 s[2:3], s[0:1], s[2:3]
	s_andn2_b64 vcc, exec, s[2:3]
	s_cbranch_vccnz .LBB0_536
	s_cmpk_gt_u32 s8, 0x83f
	s_cbranch_scc1 .Lp6_done
	s_and_b32 s22, s95, 1
	s_lshr_b32 s20, s95, 1
	s_add_u32 s12, s30, 0x40000
	s_addc_u32 s13, s31, 0
	s_add_u32 s14, s30, 0x60000
	s_addc_u32 s15, s31, 0
	s_add_u32 s44, s30, 0xf700000
	s_addc_u32 s45, s31, 0
	s_mul_i32 s10, s22, 3
	s_add_i32 s10, s10, 0
	s_lshl_b32 s10, s10, 15
	s_add_u32 s54, s36, s10
	s_addc_u32 s55, s37, 0
	s_mul_i32 s10, s22, 1
	s_add_i32 s10, s10, 1
	s_lshl_b32 s10, s10, 15
	s_add_u32 s56, s36, s10
	s_addc_u32 s57, s37, 0
	s_mul_i32 s10, s22, -1
	s_add_i32 s10, s10, 2
	s_lshl_b32 s10, s10, 15
	s_add_u32 s58, s36, s10
	s_addc_u32 s59, s37, 0
	s_mul_i32 s10, s22, -3
	s_add_i32 s10, s10, 3
	s_lshl_b32 s10, s10, 15
	s_add_u32 s66, s36, s10
	s_addc_u32 s67, s37, 0
	v_and_b32_e32 v0, 31, v176
	v_lshrrev_b32_e32 v1, 5, v176
	v_bfe_u32 v2, v0, 2, 1
	v_lshrrev_b32_e32 v9, 3, v0
	v_and_b32_e32 v10, 3, v0
	v_lshl_or_b32 v3, v9, 2, v10
	s_cmp_eq_u32 s22, 0
	s_cbranch_scc1 .Lp6_fwd
	v_sub_u32_e32 v3, 15, v3
.Lp6_fwd:
	v_lshlrev_b32_e32 v4, 11, v3
	v_lshl_add_u32 v4, v1, 4, v4
	v_lshlrev_b32_e32 v5, 5, v0
	v_lshl_add_u32 v5, v1, 4, v5
	v_lshrrev_b32_e32 v6, 1, v0
	v_lshlrev_b32_e32 v6, 3, v6
	v_mov_b32_e32 v9, 0x420000
	v_mul_lo_u32 v7, v1, v9
	v_lshl_add_u32 v7, v0, 2, v7
	v_and_b32_e32 v9, 1, v0
	v_mov_b32_e32 v10, 0x80000000
	v_cmp_eq_u32_e32 vcc, 0, v9
	s_nop 3
	v_cndmask_b32_e32 v8, 0, v10, vcc
	s_mov_b32 s27, -1
	s_mov_b32 s5, s8
	s_mov_b32 s35, 1
	s_branch .Lp6_prefetch
.Lp6_top:
	s_waitcnt vmcnt(0)
	v_mov_b64_e32 v[52:53], v[68:69]
	v_mov_b64_e32 v[54:55], v[70:71]
	v_mov_b64_e32 v[56:57], v[72:73]
	v_mov_b64_e32 v[58:59], v[74:75]
	v_mov_b64_e32 v[60:61], v[76:77]
	v_mov_b64_e32 v[62:63], v[78:79]
	v_mov_b64_e32 v[64:65], v[80:81]
	v_mov_b64_e32 v[66:67], v[82:83]
	s_mov_b32 s4, s5
	s_add_i32 s5, s5, s9
	s_cmpk_gt_u32 s5, 0x83f
	s_cbranch_scc1 .Lp6_compute
.Lp6_prefetch:
	s_lshr_b32 s6, s5, 4
	s_and_b32 s7, s5, 15
	s_lshl_b32 s11, s7, 2
	s_add_i32 s11, s11, s20
	s_lshl_b32 s11, s11, 5
	s_cmp_lt_u32 s6, 4
	s_mov_b32 s10, 0x80000
	s_cselect_b32 s33, s10, 0x1000000
	s_movk_i32 s10, 0x4000
	s_cselect_b32 s32, s10, 0xffffff00
	s_lshl_b32 s10, s6, 6
	s_add_i32 s32, s32, s10
	s_lshl_b32 s32, s32, 11
	s_add_i32 s32, s32, s11
	v_mul_lo_u32 v9, v2, s33
	v_add3_u32 v11, v4, v9, s32
	global_load_dwordx4 v[68:71], v11, s[54:55]
	global_load_dwordx4 v[72:75], v11, s[56:57]
	global_load_dwordx4 v[76:79], v11, s[58:59]
	global_load_dwordx4 v[80:83], v11, s[66:67]
	s_cmp_eq_u32 s35, 0
	s_cbranch_scc1 .Lp6_compute
	s_mov_b32 s35, 0
	s_branch .Lp6_top
.Lp6_compute:
	s_lshr_b32 s6, s4, 4
	s_and_b32 s7, s4, 15
	s_cmp_eq_u32 s7, s27
	s_cbranch_scc1 .Lp6_have_g
	s_mov_b32 s27, s7
	s_lshl_b32 s25, s7, 2
	s_add_i32 s25, s25, s20
	s_lshl_b32 s10, s25, 1
	s_add_i32 s10, s10, s22
	s_lshl_b32 s10, s10, 12
	s_add_u32 s46, s14, s10
	s_addc_u32 s47, s15, 0
	s_lshl_b32 s10, s22, 6
	s_add_i32 s10, s10, s25
	s_lshl_b32 s10, s10, 9
	s_add_u32 s48, s12, s10
	s_addc_u32 s49, s13, 0
	global_load_dwordx4 v[36:39], v5, s[46:47] offset:0
	global_load_dwordx4 v[40:43], v5, s[46:47] offset:1024
	global_load_dwordx4 v[44:47], v5, s[46:47] offset:2048
	global_load_dwordx4 v[48:51], v5, s[46:47] offset:3072
	global_load_dwordx2 v[28:29], v6, s[48:49] offset:0
	global_load_dwordx2 v[30:31], v6, s[48:49] offset:128
	global_load_dwordx2 v[32:33], v6, s[48:49] offset:256
	global_load_dwordx2 v[34:35], v6, s[48:49] offset:384
	s_waitcnt vmcnt(0)
	v_mov_b32_e32 v20, v28
	v_xor_b32_e32 v24, v8, v29
	v_mov_b32_e32 v21, v30
	v_xor_b32_e32 v25, v8, v31
	v_mov_b32_e32 v22, v32
	v_xor_b32_e32 v26, v8, v33
	v_mov_b32_e32 v23, v34
	v_xor_b32_e32 v27, v8, v35
.Lp6_have_g:
	s_mul_i32 s10, s22, 0x108
	s_add_i32 s10, s10, s6
	s_lshl_b32 s10, s10, 6
	s_add_i32 s10, s10, s25
	s_lshl_b32 s10, s10, 9
	s_add_u32 s40, s44, s10
	s_addc_u32 s41, s45, 0
	v_mov_b32_e32 v12, 0
	v_mov_b32_e32 v13, 0
	v_mov_b32_e32 v14, 0
	v_mov_b32_e32 v15, 0
	v_mfma_f32_32x32x16_f16 v[96:111], v[52:55], v[36:39], 0
	v_mfma_f32_32x32x16_f16 v[112:127], v[52:55], v[40:43], 0
	v_mfma_f32_32x32x16_f16 v[128:143], v[52:55], v[44:47], 0
	v_mfma_f32_32x32x16_f16 v[144:159], v[52:55], v[48:51], 0
	s_nop 15
	v_fma_f32 v16, v20, v12, v96
	v_fma_f32 v17, v21, v13, v112
	v_fma_f32 v18, v22, v14, v128
	v_fma_f32 v19, v23, v15, v144
	v_fmac_f32_dpp v16, v12, v24 quad_perm:[1,0,3,2] row_mask:0xf bank_mask:0xf
	v_fmac_f32_dpp v17, v13, v25 quad_perm:[1,0,3,2] row_mask:0xf bank_mask:0xf
	v_fmac_f32_dpp v18, v14, v26 quad_perm:[1,0,3,2] row_mask:0xf bank_mask:0xf
	v_fmac_f32_dpp v19, v15, v27 quad_perm:[1,0,3,2] row_mask:0xf bank_mask:0xf
	v_fma_f32 v12, v20, v16, v97
	v_fma_f32 v13, v21, v17, v113
	v_fma_f32 v14, v22, v18, v129
	v_fma_f32 v15, v23, v19, v145
	v_fmac_f32_dpp v12, v16, v24 quad_perm:[1,0,3,2] row_mask:0xf bank_mask:0xf
	v_fmac_f32_dpp v13, v17, v25 quad_perm:[1,0,3,2] row_mask:0xf bank_mask:0xf
	v_fmac_f32_dpp v14, v18, v26 quad_perm:[1,0,3,2] row_mask:0xf bank_mask:0xf
	v_fmac_f32_dpp v15, v19, v27 quad_perm:[1,0,3,2] row_mask:0xf bank_mask:0xf
	v_fma_f32 v16, v20, v12, v98
	v_fma_f32 v17, v21, v13, v114
	v_fma_f32 v18, v22, v14, v130
	v_fma_f32 v19, v23, v15, v146
	v_fmac_f32_dpp v16, v12, v24 quad_perm:[1,0,3,2] row_mask:0xf bank_mask:0xf
	v_fmac_f32_dpp v17, v13, v25 quad_perm:[1,0,3,2] row_mask:0xf bank_mask:0xf
	v_fmac_f32_dpp v18, v14, v26 quad_perm:[1,0,3,2] row_mask:0xf bank_mask:0xf
	v_fmac_f32_dpp v19, v15, v27 quad_perm:[1,0,3,2] row_mask:0xf bank_mask:0xf
	v_fma_f32 v12, v20, v16, v99
	v_fma_f32 v13, v21, v17, v115
	v_fma_f32 v14, v22, v18, v131
	v_fma_f32 v15, v23, v19, v147
	v_fmac_f32_dpp v12, v16, v24 quad_perm:[1,0,3,2] row_mask:0xf bank_mask:0xf
	v_fmac_f32_dpp v13, v17, v25 quad_perm:[1,0,3,2] row_mask:0xf bank_mask:0xf
	v_fmac_f32_dpp v14, v18, v26 quad_perm:[1,0,3,2] row_mask:0xf bank_mask:0xf
	v_fmac_f32_dpp v15, v19, v27 quad_perm:[1,0,3,2] row_mask:0xf bank_mask:0xf
	v_fma_f32 v16, v20, v12, v100
	v_fma_f32 v17, v21, v13, v116
	v_fma_f32 v18, v22, v14, v132
	v_fma_f32 v19, v23, v15, v148
	v_fmac_f32_dpp v16, v12, v24 quad_perm:[1,0,3,2] row_mask:0xf bank_mask:0xf
	v_fmac_f32_dpp v17, v13, v25 quad_perm:[1,0,3,2] row_mask:0xf bank_mask:0xf
	v_fmac_f32_dpp v18, v14, v26 quad_perm:[1,0,3,2] row_mask:0xf bank_mask:0xf
	v_fmac_f32_dpp v19, v15, v27 quad_perm:[1,0,3,2] row_mask:0xf bank_mask:0xf
	v_fma_f32 v12, v20, v16, v101
	v_fma_f32 v13, v21, v17, v117
	v_fma_f32 v14, v22, v18, v133
	v_fma_f32 v15, v23, v19, v149
	v_fmac_f32_dpp v12, v16, v24 quad_perm:[1,0,3,2] row_mask:0xf bank_mask:0xf
	v_fmac_f32_dpp v13, v17, v25 quad_perm:[1,0,3,2] row_mask:0xf bank_mask:0xf
	v_fmac_f32_dpp v14, v18, v26 quad_perm:[1,0,3,2] row_mask:0xf bank_mask:0xf
	v_fmac_f32_dpp v15, v19, v27 quad_perm:[1,0,3,2] row_mask:0xf bank_mask:0xf
	v_fma_f32 v16, v20, v12, v102
	v_fma_f32 v17, v21, v13, v118
	v_fma_f32 v18, v22, v14, v134
	v_fma_f32 v19, v23, v15, v150
	v_fmac_f32_dpp v16, v12, v24 quad_perm:[1,0,3,2] row_mask:0xf bank_mask:0xf
	v_fmac_f32_dpp v17, v13, v25 quad_perm:[1,0,3,2] row_mask:0xf bank_mask:0xf
	v_fmac_f32_dpp v18, v14, v26 quad_perm:[1,0,3,2] row_mask:0xf bank_mask:0xf
	v_fmac_f32_dpp v19, v15, v27 quad_perm:[1,0,3,2] row_mask:0xf bank_mask:0xf
	v_fma_f32 v12, v20, v16, v103
	v_fma_f32 v13, v21, v17, v119
	v_fma_f32 v14, v22, v18, v135
	v_fma_f32 v15, v23, v19, v151
	v_fmac_f32_dpp v12, v16, v24 quad_perm:[1,0,3,2] row_mask:0xf bank_mask:0xf
	v_fmac_f32_dpp v13, v17, v25 quad_perm:[1,0,3,2] row_mask:0xf bank_mask:0xf
	v_fmac_f32_dpp v14, v18, v26 quad_perm:[1,0,3,2] row_mask:0xf bank_mask:0xf
	v_fmac_f32_dpp v15, v19, v27 quad_perm:[1,0,3,2] row_mask:0xf bank_mask:0xf
	v_fma_f32 v16, v20, v12, v104
	v_fma_f32 v17, v21, v13, v120
	v_fma_f32 v18, v22, v14, v136
	v_fma_f32 v19, v23, v15, v152
	v_fmac_f32_dpp v16, v12, v24 quad_perm:[1,0,3,2] row_mask:0xf bank_mask:0xf
	v_fmac_f32_dpp v17, v13, v25 quad_perm:[1,0,3,2] row_mask:0xf bank_mask:0xf
	v_fmac_f32_dpp v18, v14, v26 quad_perm:[1,0,3,2] row_mask:0xf bank_mask:0xf
	v_fmac_f32_dpp v19, v15, v27 quad_perm:[1,0,3,2] row_mask:0xf bank_mask:0xf
	v_fma_f32 v12, v20, v16, v105
	v_fma_f32 v13, v21, v17, v121
	v_fma_f32 v14, v22, v18, v137
	v_fma_f32 v15, v23, v19, v153
	v_fmac_f32_dpp v12, v16, v24 quad_perm:[1,0,3,2] row_mask:0xf bank_mask:0xf
	v_fmac_f32_dpp v13, v17, v25 quad_perm:[1,0,3,2] row_mask:0xf bank_mask:0xf
	v_fmac_f32_dpp v14, v18, v26 quad_perm:[1,0,3,2] row_mask:0xf bank_mask:0xf
	v_fmac_f32_dpp v15, v19, v27 quad_perm:[1,0,3,2] row_mask:0xf bank_mask:0xf
	v_fma_f32 v16, v20, v12, v106
	v_fma_f32 v17, v21, v13, v122
	v_fma_f32 v18, v22, v14, v138
	v_fma_f32 v19, v23, v15, v154
	v_fmac_f32_dpp v16, v12, v24 quad_perm:[1,0,3,2] row_mask:0xf bank_mask:0xf
	v_fmac_f32_dpp v17, v13, v25 quad_perm:[1,0,3,2] row_mask:0xf bank_mask:0xf
	v_fmac_f32_dpp v18, v14, v26 quad_perm:[1,0,3,2] row_mask:0xf bank_mask:0xf
	v_fmac_f32_dpp v19, v15, v27 quad_perm:[1,0,3,2] row_mask:0xf bank_mask:0xf
	v_fma_f32 v12, v20, v16, v107
	v_fma_f32 v13, v21, v17, v123
	v_fma_f32 v14, v22, v18, v139
	v_fma_f32 v15, v23, v19, v155
	v_fmac_f32_dpp v12, v16, v24 quad_perm:[1,0,3,2] row_mask:0xf bank_mask:0xf
	v_fmac_f32_dpp v13, v17, v25 quad_perm:[1,0,3,2] row_mask:0xf bank_mask:0xf
	v_fmac_f32_dpp v14, v18, v26 quad_perm:[1,0,3,2] row_mask:0xf bank_mask:0xf
	v_fmac_f32_dpp v15, v19, v27 quad_perm:[1,0,3,2] row_mask:0xf bank_mask:0xf
	v_fma_f32 v16, v20, v12, v108
	v_fma_f32 v17, v21, v13, v124
	v_fma_f32 v18, v22, v14, v140
	v_fma_f32 v19, v23, v15, v156
	v_fmac_f32_dpp v16, v12, v24 quad_perm:[1,0,3,2] row_mask:0xf bank_mask:0xf
	v_fmac_f32_dpp v17, v13, v25 quad_perm:[1,0,3,2] row_mask:0xf bank_mask:0xf
	v_fmac_f32_dpp v18, v14, v26 quad_perm:[1,0,3,2] row_mask:0xf bank_mask:0xf
	v_fmac_f32_dpp v19, v15, v27 quad_perm:[1,0,3,2] row_mask:0xf bank_mask:0xf
	v_fma_f32 v12, v20, v16, v109
	v_fma_f32 v13, v21, v17, v125
	v_fma_f32 v14, v22, v18, v141
	v_fma_f32 v15, v23, v19, v157
	v_fmac_f32_dpp v12, v16, v24 quad_perm:[1,0,3,2] row_mask:0xf bank_mask:0xf
	v_fmac_f32_dpp v13, v17, v25 quad_perm:[1,0,3,2] row_mask:0xf bank_mask:0xf
	v_fmac_f32_dpp v14, v18, v26 quad_perm:[1,0,3,2] row_mask:0xf bank_mask:0xf
	v_fmac_f32_dpp v15, v19, v27 quad_perm:[1,0,3,2] row_mask:0xf bank_mask:0xf
	v_fma_f32 v16, v20, v12, v110
	v_fma_f32 v17, v21, v13, v126
	v_fma_f32 v18, v22, v14, v142
	v_fma_f32 v19, v23, v15, v158
	v_fmac_f32_dpp v16, v12, v24 quad_perm:[1,0,3,2] row_mask:0xf bank_mask:0xf
	v_fmac_f32_dpp v17, v13, v25 quad_perm:[1,0,3,2] row_mask:0xf bank_mask:0xf
	v_fmac_f32_dpp v18, v14, v26 quad_perm:[1,0,3,2] row_mask:0xf bank_mask:0xf
	v_fmac_f32_dpp v19, v15, v27 quad_perm:[1,0,3,2] row_mask:0xf bank_mask:0xf
	v_fma_f32 v12, v20, v16, v111
	v_fma_f32 v13, v21, v17, v127
	v_fma_f32 v14, v22, v18, v143
	v_fma_f32 v15, v23, v19, v159
	v_fmac_f32_dpp v12, v16, v24 quad_perm:[1,0,3,2] row_mask:0xf bank_mask:0xf
	v_fmac_f32_dpp v13, v17, v25 quad_perm:[1,0,3,2] row_mask:0xf bank_mask:0xf
	v_fmac_f32_dpp v14, v18, v26 quad_perm:[1,0,3,2] row_mask:0xf bank_mask:0xf
	v_fmac_f32_dpp v15, v19, v27 quad_perm:[1,0,3,2] row_mask:0xf bank_mask:0xf
	v_mfma_f32_32x32x16_f16 v[96:111], v[56:59], v[36:39], 0
	v_mfma_f32_32x32x16_f16 v[112:127], v[56:59], v[40:43], 0
	v_mfma_f32_32x32x16_f16 v[128:143], v[56:59], v[44:47], 0
	v_mfma_f32_32x32x16_f16 v[144:159], v[56:59], v[48:51], 0
	s_nop 15
	v_fma_f32 v16, v20, v12, v96
	v_fma_f32 v17, v21, v13, v112
	v_fma_f32 v18, v22, v14, v128
	v_fma_f32 v19, v23, v15, v144
	v_fmac_f32_dpp v16, v12, v24 quad_perm:[1,0,3,2] row_mask:0xf bank_mask:0xf
	v_fmac_f32_dpp v17, v13, v25 quad_perm:[1,0,3,2] row_mask:0xf bank_mask:0xf
	v_fmac_f32_dpp v18, v14, v26 quad_perm:[1,0,3,2] row_mask:0xf bank_mask:0xf
	v_fmac_f32_dpp v19, v15, v27 quad_perm:[1,0,3,2] row_mask:0xf bank_mask:0xf
	v_fma_f32 v12, v20, v16, v97
	v_fma_f32 v13, v21, v17, v113
	v_fma_f32 v14, v22, v18, v129
	v_fma_f32 v15, v23, v19, v145
	v_fmac_f32_dpp v12, v16, v24 quad_perm:[1,0,3,2] row_mask:0xf bank_mask:0xf
	v_fmac_f32_dpp v13, v17, v25 quad_perm:[1,0,3,2] row_mask:0xf bank_mask:0xf
	v_fmac_f32_dpp v14, v18, v26 quad_perm:[1,0,3,2] row_mask:0xf bank_mask:0xf
	v_fmac_f32_dpp v15, v19, v27 quad_perm:[1,0,3,2] row_mask:0xf bank_mask:0xf
	v_fma_f32 v16, v20, v12, v98
	v_fma_f32 v17, v21, v13, v114
	v_fma_f32 v18, v22, v14, v130
	v_fma_f32 v19, v23, v15, v146
	v_fmac_f32_dpp v16, v12, v24 quad_perm:[1,0,3,2] row_mask:0xf bank_mask:0xf
	v_fmac_f32_dpp v17, v13, v25 quad_perm:[1,0,3,2] row_mask:0xf bank_mask:0xf
	v_fmac_f32_dpp v18, v14, v26 quad_perm:[1,0,3,2] row_mask:0xf bank_mask:0xf
	v_fmac_f32_dpp v19, v15, v27 quad_perm:[1,0,3,2] row_mask:0xf bank_mask:0xf
	v_fma_f32 v12, v20, v16, v99
	v_fma_f32 v13, v21, v17, v115
	v_fma_f32 v14, v22, v18, v131
	v_fma_f32 v15, v23, v19, v147
	v_fmac_f32_dpp v12, v16, v24 quad_perm:[1,0,3,2] row_mask:0xf bank_mask:0xf
	v_fmac_f32_dpp v13, v17, v25 quad_perm:[1,0,3,2] row_mask:0xf bank_mask:0xf
	v_fmac_f32_dpp v14, v18, v26 quad_perm:[1,0,3,2] row_mask:0xf bank_mask:0xf
	v_fmac_f32_dpp v15, v19, v27 quad_perm:[1,0,3,2] row_mask:0xf bank_mask:0xf
	v_fma_f32 v16, v20, v12, v100
	v_fma_f32 v17, v21, v13, v116
	v_fma_f32 v18, v22, v14, v132
	v_fma_f32 v19, v23, v15, v148
	v_fmac_f32_dpp v16, v12, v24 quad_perm:[1,0,3,2] row_mask:0xf bank_mask:0xf
	v_fmac_f32_dpp v17, v13, v25 quad_perm:[1,0,3,2] row_mask:0xf bank_mask:0xf
	v_fmac_f32_dpp v18, v14, v26 quad_perm:[1,0,3,2] row_mask:0xf bank_mask:0xf
	v_fmac_f32_dpp v19, v15, v27 quad_perm:[1,0,3,2] row_mask:0xf bank_mask:0xf
	v_fma_f32 v12, v20, v16, v101
	v_fma_f32 v13, v21, v17, v117
	v_fma_f32 v14, v22, v18, v133
	v_fma_f32 v15, v23, v19, v149
	v_fmac_f32_dpp v12, v16, v24 quad_perm:[1,0,3,2] row_mask:0xf bank_mask:0xf
	v_fmac_f32_dpp v13, v17, v25 quad_perm:[1,0,3,2] row_mask:0xf bank_mask:0xf
	v_fmac_f32_dpp v14, v18, v26 quad_perm:[1,0,3,2] row_mask:0xf bank_mask:0xf
	v_fmac_f32_dpp v15, v19, v27 quad_perm:[1,0,3,2] row_mask:0xf bank_mask:0xf
	v_fma_f32 v16, v20, v12, v102
	v_fma_f32 v17, v21, v13, v118
	v_fma_f32 v18, v22, v14, v134
	v_fma_f32 v19, v23, v15, v150
	v_fmac_f32_dpp v16, v12, v24 quad_perm:[1,0,3,2] row_mask:0xf bank_mask:0xf
	v_fmac_f32_dpp v17, v13, v25 quad_perm:[1,0,3,2] row_mask:0xf bank_mask:0xf
	v_fmac_f32_dpp v18, v14, v26 quad_perm:[1,0,3,2] row_mask:0xf bank_mask:0xf
	v_fmac_f32_dpp v19, v15, v27 quad_perm:[1,0,3,2] row_mask:0xf bank_mask:0xf
	v_fma_f32 v12, v20, v16, v103
	v_fma_f32 v13, v21, v17, v119
	v_fma_f32 v14, v22, v18, v135
	v_fma_f32 v15, v23, v19, v151
	v_fmac_f32_dpp v12, v16, v24 quad_perm:[1,0,3,2] row_mask:0xf bank_mask:0xf
	v_fmac_f32_dpp v13, v17, v25 quad_perm:[1,0,3,2] row_mask:0xf bank_mask:0xf
	v_fmac_f32_dpp v14, v18, v26 quad_perm:[1,0,3,2] row_mask:0xf bank_mask:0xf
	v_fmac_f32_dpp v15, v19, v27 quad_perm:[1,0,3,2] row_mask:0xf bank_mask:0xf
	v_fma_f32 v16, v20, v12, v104
	v_fma_f32 v17, v21, v13, v120
	v_fma_f32 v18, v22, v14, v136
	v_fma_f32 v19, v23, v15, v152
	v_fmac_f32_dpp v16, v12, v24 quad_perm:[1,0,3,2] row_mask:0xf bank_mask:0xf
	v_fmac_f32_dpp v17, v13, v25 quad_perm:[1,0,3,2] row_mask:0xf bank_mask:0xf
	v_fmac_f32_dpp v18, v14, v26 quad_perm:[1,0,3,2] row_mask:0xf bank_mask:0xf
	v_fmac_f32_dpp v19, v15, v27 quad_perm:[1,0,3,2] row_mask:0xf bank_mask:0xf
	v_fma_f32 v12, v20, v16, v105
	v_fma_f32 v13, v21, v17, v121
	v_fma_f32 v14, v22, v18, v137
	v_fma_f32 v15, v23, v19, v153
	v_fmac_f32_dpp v12, v16, v24 quad_perm:[1,0,3,2] row_mask:0xf bank_mask:0xf
	v_fmac_f32_dpp v13, v17, v25 quad_perm:[1,0,3,2] row_mask:0xf bank_mask:0xf
	v_fmac_f32_dpp v14, v18, v26 quad_perm:[1,0,3,2] row_mask:0xf bank_mask:0xf
	v_fmac_f32_dpp v15, v19, v27 quad_perm:[1,0,3,2] row_mask:0xf bank_mask:0xf
	v_fma_f32 v16, v20, v12, v106
	v_fma_f32 v17, v21, v13, v122
	v_fma_f32 v18, v22, v14, v138
	v_fma_f32 v19, v23, v15, v154
	v_fmac_f32_dpp v16, v12, v24 quad_perm:[1,0,3,2] row_mask:0xf bank_mask:0xf
	v_fmac_f32_dpp v17, v13, v25 quad_perm:[1,0,3,2] row_mask:0xf bank_mask:0xf
	v_fmac_f32_dpp v18, v14, v26 quad_perm:[1,0,3,2] row_mask:0xf bank_mask:0xf
	v_fmac_f32_dpp v19, v15, v27 quad_perm:[1,0,3,2] row_mask:0xf bank_mask:0xf
	v_fma_f32 v12, v20, v16, v107
	v_fma_f32 v13, v21, v17, v123
	v_fma_f32 v14, v22, v18, v139
	v_fma_f32 v15, v23, v19, v155
	v_fmac_f32_dpp v12, v16, v24 quad_perm:[1,0,3,2] row_mask:0xf bank_mask:0xf
	v_fmac_f32_dpp v13, v17, v25 quad_perm:[1,0,3,2] row_mask:0xf bank_mask:0xf
	v_fmac_f32_dpp v14, v18, v26 quad_perm:[1,0,3,2] row_mask:0xf bank_mask:0xf
	v_fmac_f32_dpp v15, v19, v27 quad_perm:[1,0,3,2] row_mask:0xf bank_mask:0xf
	v_fma_f32 v16, v20, v12, v108
	v_fma_f32 v17, v21, v13, v124
	v_fma_f32 v18, v22, v14, v140
	v_fma_f32 v19, v23, v15, v156
	v_fmac_f32_dpp v16, v12, v24 quad_perm:[1,0,3,2] row_mask:0xf bank_mask:0xf
	v_fmac_f32_dpp v17, v13, v25 quad_perm:[1,0,3,2] row_mask:0xf bank_mask:0xf
	v_fmac_f32_dpp v18, v14, v26 quad_perm:[1,0,3,2] row_mask:0xf bank_mask:0xf
	v_fmac_f32_dpp v19, v15, v27 quad_perm:[1,0,3,2] row_mask:0xf bank_mask:0xf
	v_fma_f32 v12, v20, v16, v109
	v_fma_f32 v13, v21, v17, v125
	v_fma_f32 v14, v22, v18, v141
	v_fma_f32 v15, v23, v19, v157
	v_fmac_f32_dpp v12, v16, v24 quad_perm:[1,0,3,2] row_mask:0xf bank_mask:0xf
	v_fmac_f32_dpp v13, v17, v25 quad_perm:[1,0,3,2] row_mask:0xf bank_mask:0xf
	v_fmac_f32_dpp v14, v18, v26 quad_perm:[1,0,3,2] row_mask:0xf bank_mask:0xf
	v_fmac_f32_dpp v15, v19, v27 quad_perm:[1,0,3,2] row_mask:0xf bank_mask:0xf
	v_fma_f32 v16, v20, v12, v110
	v_fma_f32 v17, v21, v13, v126
	v_fma_f32 v18, v22, v14, v142
	v_fma_f32 v19, v23, v15, v158
	v_fmac_f32_dpp v16, v12, v24 quad_perm:[1,0,3,2] row_mask:0xf bank_mask:0xf
	v_fmac_f32_dpp v17, v13, v25 quad_perm:[1,0,3,2] row_mask:0xf bank_mask:0xf
	v_fmac_f32_dpp v18, v14, v26 quad_perm:[1,0,3,2] row_mask:0xf bank_mask:0xf
	v_fmac_f32_dpp v19, v15, v27 quad_perm:[1,0,3,2] row_mask:0xf bank_mask:0xf
	v_fma_f32 v12, v20, v16, v111
	v_fma_f32 v13, v21, v17, v127
	v_fma_f32 v14, v22, v18, v143
	v_fma_f32 v15, v23, v19, v159
	v_fmac_f32_dpp v12, v16, v24 quad_perm:[1,0,3,2] row_mask:0xf bank_mask:0xf
	v_fmac_f32_dpp v13, v17, v25 quad_perm:[1,0,3,2] row_mask:0xf bank_mask:0xf
	v_fmac_f32_dpp v14, v18, v26 quad_perm:[1,0,3,2] row_mask:0xf bank_mask:0xf
	v_fmac_f32_dpp v15, v19, v27 quad_perm:[1,0,3,2] row_mask:0xf bank_mask:0xf
	v_mfma_f32_32x32x16_f16 v[96:111], v[60:63], v[36:39], 0
	v_mfma_f32_32x32x16_f16 v[112:127], v[60:63], v[40:43], 0
	v_mfma_f32_32x32x16_f16 v[128:143], v[60:63], v[44:47], 0
	v_mfma_f32_32x32x16_f16 v[144:159], v[60:63], v[48:51], 0
	s_nop 15
	v_fma_f32 v16, v20, v12, v96
	v_fma_f32 v17, v21, v13, v112
	v_fma_f32 v18, v22, v14, v128
	v_fma_f32 v19, v23, v15, v144
	v_fmac_f32_dpp v16, v12, v24 quad_perm:[1,0,3,2] row_mask:0xf bank_mask:0xf
	v_fmac_f32_dpp v17, v13, v25 quad_perm:[1,0,3,2] row_mask:0xf bank_mask:0xf
	v_fmac_f32_dpp v18, v14, v26 quad_perm:[1,0,3,2] row_mask:0xf bank_mask:0xf
	v_fmac_f32_dpp v19, v15, v27 quad_perm:[1,0,3,2] row_mask:0xf bank_mask:0xf
	v_fma_f32 v12, v20, v16, v97
	v_fma_f32 v13, v21, v17, v113
	v_fma_f32 v14, v22, v18, v129
	v_fma_f32 v15, v23, v19, v145
	v_fmac_f32_dpp v12, v16, v24 quad_perm:[1,0,3,2] row_mask:0xf bank_mask:0xf
	v_fmac_f32_dpp v13, v17, v25 quad_perm:[1,0,3,2] row_mask:0xf bank_mask:0xf
	v_fmac_f32_dpp v14, v18, v26 quad_perm:[1,0,3,2] row_mask:0xf bank_mask:0xf
	v_fmac_f32_dpp v15, v19, v27 quad_perm:[1,0,3,2] row_mask:0xf bank_mask:0xf
	v_fma_f32 v16, v20, v12, v98
	v_fma_f32 v17, v21, v13, v114
	v_fma_f32 v18, v22, v14, v130
	v_fma_f32 v19, v23, v15, v146
	v_fmac_f32_dpp v16, v12, v24 quad_perm:[1,0,3,2] row_mask:0xf bank_mask:0xf
	v_fmac_f32_dpp v17, v13, v25 quad_perm:[1,0,3,2] row_mask:0xf bank_mask:0xf
	v_fmac_f32_dpp v18, v14, v26 quad_perm:[1,0,3,2] row_mask:0xf bank_mask:0xf
	v_fmac_f32_dpp v19, v15, v27 quad_perm:[1,0,3,2] row_mask:0xf bank_mask:0xf
	v_fma_f32 v12, v20, v16, v99
	v_fma_f32 v13, v21, v17, v115
	v_fma_f32 v14, v22, v18, v131
	v_fma_f32 v15, v23, v19, v147
	v_fmac_f32_dpp v12, v16, v24 quad_perm:[1,0,3,2] row_mask:0xf bank_mask:0xf
	v_fmac_f32_dpp v13, v17, v25 quad_perm:[1,0,3,2] row_mask:0xf bank_mask:0xf
	v_fmac_f32_dpp v14, v18, v26 quad_perm:[1,0,3,2] row_mask:0xf bank_mask:0xf
	v_fmac_f32_dpp v15, v19, v27 quad_perm:[1,0,3,2] row_mask:0xf bank_mask:0xf
	v_fma_f32 v16, v20, v12, v100
	v_fma_f32 v17, v21, v13, v116
	v_fma_f32 v18, v22, v14, v132
	v_fma_f32 v19, v23, v15, v148
	v_fmac_f32_dpp v16, v12, v24 quad_perm:[1,0,3,2] row_mask:0xf bank_mask:0xf
	v_fmac_f32_dpp v17, v13, v25 quad_perm:[1,0,3,2] row_mask:0xf bank_mask:0xf
	v_fmac_f32_dpp v18, v14, v26 quad_perm:[1,0,3,2] row_mask:0xf bank_mask:0xf
	v_fmac_f32_dpp v19, v15, v27 quad_perm:[1,0,3,2] row_mask:0xf bank_mask:0xf
	v_fma_f32 v12, v20, v16, v101
	v_fma_f32 v13, v21, v17, v117
	v_fma_f32 v14, v22, v18, v133
	v_fma_f32 v15, v23, v19, v149
	v_fmac_f32_dpp v12, v16, v24 quad_perm:[1,0,3,2] row_mask:0xf bank_mask:0xf
	v_fmac_f32_dpp v13, v17, v25 quad_perm:[1,0,3,2] row_mask:0xf bank_mask:0xf
	v_fmac_f32_dpp v14, v18, v26 quad_perm:[1,0,3,2] row_mask:0xf bank_mask:0xf
	v_fmac_f32_dpp v15, v19, v27 quad_perm:[1,0,3,2] row_mask:0xf bank_mask:0xf
	v_fma_f32 v16, v20, v12, v102
	v_fma_f32 v17, v21, v13, v118
	v_fma_f32 v18, v22, v14, v134
	v_fma_f32 v19, v23, v15, v150
	v_fmac_f32_dpp v16, v12, v24 quad_perm:[1,0,3,2] row_mask:0xf bank_mask:0xf
	v_fmac_f32_dpp v17, v13, v25 quad_perm:[1,0,3,2] row_mask:0xf bank_mask:0xf
	v_fmac_f32_dpp v18, v14, v26 quad_perm:[1,0,3,2] row_mask:0xf bank_mask:0xf
	v_fmac_f32_dpp v19, v15, v27 quad_perm:[1,0,3,2] row_mask:0xf bank_mask:0xf
	v_fma_f32 v12, v20, v16, v103
	v_fma_f32 v13, v21, v17, v119
	v_fma_f32 v14, v22, v18, v135
	v_fma_f32 v15, v23, v19, v151
	v_fmac_f32_dpp v12, v16, v24 quad_perm:[1,0,3,2] row_mask:0xf bank_mask:0xf
	v_fmac_f32_dpp v13, v17, v25 quad_perm:[1,0,3,2] row_mask:0xf bank_mask:0xf
	v_fmac_f32_dpp v14, v18, v26 quad_perm:[1,0,3,2] row_mask:0xf bank_mask:0xf
	v_fmac_f32_dpp v15, v19, v27 quad_perm:[1,0,3,2] row_mask:0xf bank_mask:0xf
	v_fma_f32 v16, v20, v12, v104
	v_fma_f32 v17, v21, v13, v120
	v_fma_f32 v18, v22, v14, v136
	v_fma_f32 v19, v23, v15, v152
	v_fmac_f32_dpp v16, v12, v24 quad_perm:[1,0,3,2] row_mask:0xf bank_mask:0xf
	v_fmac_f32_dpp v17, v13, v25 quad_perm:[1,0,3,2] row_mask:0xf bank_mask:0xf
	v_fmac_f32_dpp v18, v14, v26 quad_perm:[1,0,3,2] row_mask:0xf bank_mask:0xf
	v_fmac_f32_dpp v19, v15, v27 quad_perm:[1,0,3,2] row_mask:0xf bank_mask:0xf
	v_fma_f32 v12, v20, v16, v105
	v_fma_f32 v13, v21, v17, v121
	v_fma_f32 v14, v22, v18, v137
	v_fma_f32 v15, v23, v19, v153
	v_fmac_f32_dpp v12, v16, v24 quad_perm:[1,0,3,2] row_mask:0xf bank_mask:0xf
	v_fmac_f32_dpp v13, v17, v25 quad_perm:[1,0,3,2] row_mask:0xf bank_mask:0xf
	v_fmac_f32_dpp v14, v18, v26 quad_perm:[1,0,3,2] row_mask:0xf bank_mask:0xf
	v_fmac_f32_dpp v15, v19, v27 quad_perm:[1,0,3,2] row_mask:0xf bank_mask:0xf
	v_fma_f32 v16, v20, v12, v106
	v_fma_f32 v17, v21, v13, v122
	v_fma_f32 v18, v22, v14, v138
	v_fma_f32 v19, v23, v15, v154
	v_fmac_f32_dpp v16, v12, v24 quad_perm:[1,0,3,2] row_mask:0xf bank_mask:0xf
	v_fmac_f32_dpp v17, v13, v25 quad_perm:[1,0,3,2] row_mask:0xf bank_mask:0xf
	v_fmac_f32_dpp v18, v14, v26 quad_perm:[1,0,3,2] row_mask:0xf bank_mask:0xf
	v_fmac_f32_dpp v19, v15, v27 quad_perm:[1,0,3,2] row_mask:0xf bank_mask:0xf
	v_fma_f32 v12, v20, v16, v107
	v_fma_f32 v13, v21, v17, v123
	v_fma_f32 v14, v22, v18, v139
	v_fma_f32 v15, v23, v19, v155
	v_fmac_f32_dpp v12, v16, v24 quad_perm:[1,0,3,2] row_mask:0xf bank_mask:0xf
	v_fmac_f32_dpp v13, v17, v25 quad_perm:[1,0,3,2] row_mask:0xf bank_mask:0xf
	v_fmac_f32_dpp v14, v18, v26 quad_perm:[1,0,3,2] row_mask:0xf bank_mask:0xf
	v_fmac_f32_dpp v15, v19, v27 quad_perm:[1,0,3,2] row_mask:0xf bank_mask:0xf
	v_fma_f32 v16, v20, v12, v108
	v_fma_f32 v17, v21, v13, v124
	v_fma_f32 v18, v22, v14, v140
	v_fma_f32 v19, v23, v15, v156
	v_fmac_f32_dpp v16, v12, v24 quad_perm:[1,0,3,2] row_mask:0xf bank_mask:0xf
	v_fmac_f32_dpp v17, v13, v25 quad_perm:[1,0,3,2] row_mask:0xf bank_mask:0xf
	v_fmac_f32_dpp v18, v14, v26 quad_perm:[1,0,3,2] row_mask:0xf bank_mask:0xf
	v_fmac_f32_dpp v19, v15, v27 quad_perm:[1,0,3,2] row_mask:0xf bank_mask:0xf
	v_fma_f32 v12, v20, v16, v109
	v_fma_f32 v13, v21, v17, v125
	v_fma_f32 v14, v22, v18, v141
	v_fma_f32 v15, v23, v19, v157
	v_fmac_f32_dpp v12, v16, v24 quad_perm:[1,0,3,2] row_mask:0xf bank_mask:0xf
	v_fmac_f32_dpp v13, v17, v25 quad_perm:[1,0,3,2] row_mask:0xf bank_mask:0xf
	v_fmac_f32_dpp v14, v18, v26 quad_perm:[1,0,3,2] row_mask:0xf bank_mask:0xf
	v_fmac_f32_dpp v15, v19, v27 quad_perm:[1,0,3,2] row_mask:0xf bank_mask:0xf
	v_fma_f32 v16, v20, v12, v110
	v_fma_f32 v17, v21, v13, v126
	v_fma_f32 v18, v22, v14, v142
	v_fma_f32 v19, v23, v15, v158
	v_fmac_f32_dpp v16, v12, v24 quad_perm:[1,0,3,2] row_mask:0xf bank_mask:0xf
	v_fmac_f32_dpp v17, v13, v25 quad_perm:[1,0,3,2] row_mask:0xf bank_mask:0xf
	v_fmac_f32_dpp v18, v14, v26 quad_perm:[1,0,3,2] row_mask:0xf bank_mask:0xf
	v_fmac_f32_dpp v19, v15, v27 quad_perm:[1,0,3,2] row_mask:0xf bank_mask:0xf
	v_fma_f32 v12, v20, v16, v111
	v_fma_f32 v13, v21, v17, v127
	v_fma_f32 v14, v22, v18, v143
	v_fma_f32 v15, v23, v19, v159
	v_fmac_f32_dpp v12, v16, v24 quad_perm:[1,0,3,2] row_mask:0xf bank_mask:0xf
	v_fmac_f32_dpp v13, v17, v25 quad_perm:[1,0,3,2] row_mask:0xf bank_mask:0xf
	v_fmac_f32_dpp v14, v18, v26 quad_perm:[1,0,3,2] row_mask:0xf bank_mask:0xf
	v_fmac_f32_dpp v15, v19, v27 quad_perm:[1,0,3,2] row_mask:0xf bank_mask:0xf
	v_mfma_f32_32x32x16_f16 v[96:111], v[64:67], v[36:39], 0
	v_mfma_f32_32x32x16_f16 v[112:127], v[64:67], v[40:43], 0
	v_mfma_f32_32x32x16_f16 v[128:143], v[64:67], v[44:47], 0
	v_mfma_f32_32x32x16_f16 v[144:159], v[64:67], v[48:51], 0
	s_nop 15
	v_fma_f32 v16, v20, v12, v96
	v_fma_f32 v17, v21, v13, v112
	v_fma_f32 v18, v22, v14, v128
	v_fma_f32 v19, v23, v15, v144
	v_fmac_f32_dpp v16, v12, v24 quad_perm:[1,0,3,2] row_mask:0xf bank_mask:0xf
	v_fmac_f32_dpp v17, v13, v25 quad_perm:[1,0,3,2] row_mask:0xf bank_mask:0xf
	v_fmac_f32_dpp v18, v14, v26 quad_perm:[1,0,3,2] row_mask:0xf bank_mask:0xf
	v_fmac_f32_dpp v19, v15, v27 quad_perm:[1,0,3,2] row_mask:0xf bank_mask:0xf
	v_fma_f32 v12, v20, v16, v97
	v_fma_f32 v13, v21, v17, v113
	v_fma_f32 v14, v22, v18, v129
	v_fma_f32 v15, v23, v19, v145
	v_fmac_f32_dpp v12, v16, v24 quad_perm:[1,0,3,2] row_mask:0xf bank_mask:0xf
	v_fmac_f32_dpp v13, v17, v25 quad_perm:[1,0,3,2] row_mask:0xf bank_mask:0xf
	v_fmac_f32_dpp v14, v18, v26 quad_perm:[1,0,3,2] row_mask:0xf bank_mask:0xf
	v_fmac_f32_dpp v15, v19, v27 quad_perm:[1,0,3,2] row_mask:0xf bank_mask:0xf
	v_fma_f32 v16, v20, v12, v98
	v_fma_f32 v17, v21, v13, v114
	v_fma_f32 v18, v22, v14, v130
	v_fma_f32 v19, v23, v15, v146
	v_fmac_f32_dpp v16, v12, v24 quad_perm:[1,0,3,2] row_mask:0xf bank_mask:0xf
	v_fmac_f32_dpp v17, v13, v25 quad_perm:[1,0,3,2] row_mask:0xf bank_mask:0xf
	v_fmac_f32_dpp v18, v14, v26 quad_perm:[1,0,3,2] row_mask:0xf bank_mask:0xf
	v_fmac_f32_dpp v19, v15, v27 quad_perm:[1,0,3,2] row_mask:0xf bank_mask:0xf
	v_fma_f32 v12, v20, v16, v99
	v_fma_f32 v13, v21, v17, v115
	v_fma_f32 v14, v22, v18, v131
	v_fma_f32 v15, v23, v19, v147
	v_fmac_f32_dpp v12, v16, v24 quad_perm:[1,0,3,2] row_mask:0xf bank_mask:0xf
	v_fmac_f32_dpp v13, v17, v25 quad_perm:[1,0,3,2] row_mask:0xf bank_mask:0xf
	v_fmac_f32_dpp v14, v18, v26 quad_perm:[1,0,3,2] row_mask:0xf bank_mask:0xf
	v_fmac_f32_dpp v15, v19, v27 quad_perm:[1,0,3,2] row_mask:0xf bank_mask:0xf
	v_fma_f32 v16, v20, v12, v100
	v_fma_f32 v17, v21, v13, v116
	v_fma_f32 v18, v22, v14, v132
	v_fma_f32 v19, v23, v15, v148
	v_fmac_f32_dpp v16, v12, v24 quad_perm:[1,0,3,2] row_mask:0xf bank_mask:0xf
	v_fmac_f32_dpp v17, v13, v25 quad_perm:[1,0,3,2] row_mask:0xf bank_mask:0xf
	v_fmac_f32_dpp v18, v14, v26 quad_perm:[1,0,3,2] row_mask:0xf bank_mask:0xf
	v_fmac_f32_dpp v19, v15, v27 quad_perm:[1,0,3,2] row_mask:0xf bank_mask:0xf
	v_fma_f32 v12, v20, v16, v101
	v_fma_f32 v13, v21, v17, v117
	v_fma_f32 v14, v22, v18, v133
	v_fma_f32 v15, v23, v19, v149
	v_fmac_f32_dpp v12, v16, v24 quad_perm:[1,0,3,2] row_mask:0xf bank_mask:0xf
	v_fmac_f32_dpp v13, v17, v25 quad_perm:[1,0,3,2] row_mask:0xf bank_mask:0xf
	v_fmac_f32_dpp v14, v18, v26 quad_perm:[1,0,3,2] row_mask:0xf bank_mask:0xf
	v_fmac_f32_dpp v15, v19, v27 quad_perm:[1,0,3,2] row_mask:0xf bank_mask:0xf
	v_fma_f32 v16, v20, v12, v102
	v_fma_f32 v17, v21, v13, v118
	v_fma_f32 v18, v22, v14, v134
	v_fma_f32 v19, v23, v15, v150
	v_fmac_f32_dpp v16, v12, v24 quad_perm:[1,0,3,2] row_mask:0xf bank_mask:0xf
	v_fmac_f32_dpp v17, v13, v25 quad_perm:[1,0,3,2] row_mask:0xf bank_mask:0xf
	v_fmac_f32_dpp v18, v14, v26 quad_perm:[1,0,3,2] row_mask:0xf bank_mask:0xf
	v_fmac_f32_dpp v19, v15, v27 quad_perm:[1,0,3,2] row_mask:0xf bank_mask:0xf
	v_fma_f32 v12, v20, v16, v103
	v_fma_f32 v13, v21, v17, v119
	v_fma_f32 v14, v22, v18, v135
	v_fma_f32 v15, v23, v19, v151
	v_fmac_f32_dpp v12, v16, v24 quad_perm:[1,0,3,2] row_mask:0xf bank_mask:0xf
	v_fmac_f32_dpp v13, v17, v25 quad_perm:[1,0,3,2] row_mask:0xf bank_mask:0xf
	v_fmac_f32_dpp v14, v18, v26 quad_perm:[1,0,3,2] row_mask:0xf bank_mask:0xf
	v_fmac_f32_dpp v15, v19, v27 quad_perm:[1,0,3,2] row_mask:0xf bank_mask:0xf
	v_fma_f32 v16, v20, v12, v104
	v_fma_f32 v17, v21, v13, v120
	v_fma_f32 v18, v22, v14, v136
	v_fma_f32 v19, v23, v15, v152
	v_fmac_f32_dpp v16, v12, v24 quad_perm:[1,0,3,2] row_mask:0xf bank_mask:0xf
	v_fmac_f32_dpp v17, v13, v25 quad_perm:[1,0,3,2] row_mask:0xf bank_mask:0xf
	v_fmac_f32_dpp v18, v14, v26 quad_perm:[1,0,3,2] row_mask:0xf bank_mask:0xf
	v_fmac_f32_dpp v19, v15, v27 quad_perm:[1,0,3,2] row_mask:0xf bank_mask:0xf
	v_fma_f32 v12, v20, v16, v105
	v_fma_f32 v13, v21, v17, v121
	v_fma_f32 v14, v22, v18, v137
	v_fma_f32 v15, v23, v19, v153
	v_fmac_f32_dpp v12, v16, v24 quad_perm:[1,0,3,2] row_mask:0xf bank_mask:0xf
	v_fmac_f32_dpp v13, v17, v25 quad_perm:[1,0,3,2] row_mask:0xf bank_mask:0xf
	v_fmac_f32_dpp v14, v18, v26 quad_perm:[1,0,3,2] row_mask:0xf bank_mask:0xf
	v_fmac_f32_dpp v15, v19, v27 quad_perm:[1,0,3,2] row_mask:0xf bank_mask:0xf
	v_fma_f32 v16, v20, v12, v106
	v_fma_f32 v17, v21, v13, v122
	v_fma_f32 v18, v22, v14, v138
	v_fma_f32 v19, v23, v15, v154
	v_fmac_f32_dpp v16, v12, v24 quad_perm:[1,0,3,2] row_mask:0xf bank_mask:0xf
	v_fmac_f32_dpp v17, v13, v25 quad_perm:[1,0,3,2] row_mask:0xf bank_mask:0xf
	v_fmac_f32_dpp v18, v14, v26 quad_perm:[1,0,3,2] row_mask:0xf bank_mask:0xf
	v_fmac_f32_dpp v19, v15, v27 quad_perm:[1,0,3,2] row_mask:0xf bank_mask:0xf
	v_fma_f32 v12, v20, v16, v107
	v_fma_f32 v13, v21, v17, v123
	v_fma_f32 v14, v22, v18, v139
	v_fma_f32 v15, v23, v19, v155
	v_fmac_f32_dpp v12, v16, v24 quad_perm:[1,0,3,2] row_mask:0xf bank_mask:0xf
	v_fmac_f32_dpp v13, v17, v25 quad_perm:[1,0,3,2] row_mask:0xf bank_mask:0xf
	v_fmac_f32_dpp v14, v18, v26 quad_perm:[1,0,3,2] row_mask:0xf bank_mask:0xf
	v_fmac_f32_dpp v15, v19, v27 quad_perm:[1,0,3,2] row_mask:0xf bank_mask:0xf
	v_fma_f32 v16, v20, v12, v108
	v_fma_f32 v17, v21, v13, v124
	v_fma_f32 v18, v22, v14, v140
	v_fma_f32 v19, v23, v15, v156
	v_fmac_f32_dpp v16, v12, v24 quad_perm:[1,0,3,2] row_mask:0xf bank_mask:0xf
	v_fmac_f32_dpp v17, v13, v25 quad_perm:[1,0,3,2] row_mask:0xf bank_mask:0xf
	v_fmac_f32_dpp v18, v14, v26 quad_perm:[1,0,3,2] row_mask:0xf bank_mask:0xf
	v_fmac_f32_dpp v19, v15, v27 quad_perm:[1,0,3,2] row_mask:0xf bank_mask:0xf
	v_fma_f32 v12, v20, v16, v109
	v_fma_f32 v13, v21, v17, v125
	v_fma_f32 v14, v22, v18, v141
	v_fma_f32 v15, v23, v19, v157
	v_fmac_f32_dpp v12, v16, v24 quad_perm:[1,0,3,2] row_mask:0xf bank_mask:0xf
	v_fmac_f32_dpp v13, v17, v25 quad_perm:[1,0,3,2] row_mask:0xf bank_mask:0xf
	v_fmac_f32_dpp v14, v18, v26 quad_perm:[1,0,3,2] row_mask:0xf bank_mask:0xf
	v_fmac_f32_dpp v15, v19, v27 quad_perm:[1,0,3,2] row_mask:0xf bank_mask:0xf
	v_fma_f32 v16, v20, v12, v110
	v_fma_f32 v17, v21, v13, v126
	v_fma_f32 v18, v22, v14, v142
	v_fma_f32 v19, v23, v15, v158
	v_fmac_f32_dpp v16, v12, v24 quad_perm:[1,0,3,2] row_mask:0xf bank_mask:0xf
	v_fmac_f32_dpp v17, v13, v25 quad_perm:[1,0,3,2] row_mask:0xf bank_mask:0xf
	v_fmac_f32_dpp v18, v14, v26 quad_perm:[1,0,3,2] row_mask:0xf bank_mask:0xf
	v_fmac_f32_dpp v19, v15, v27 quad_perm:[1,0,3,2] row_mask:0xf bank_mask:0xf
	v_fma_f32 v12, v20, v16, v111
	v_fma_f32 v13, v21, v17, v127
	v_fma_f32 v14, v22, v18, v143
	v_fma_f32 v15, v23, v19, v159
	v_fmac_f32_dpp v12, v16, v24 quad_perm:[1,0,3,2] row_mask:0xf bank_mask:0xf
	v_fmac_f32_dpp v13, v17, v25 quad_perm:[1,0,3,2] row_mask:0xf bank_mask:0xf
	v_fmac_f32_dpp v14, v18, v26 quad_perm:[1,0,3,2] row_mask:0xf bank_mask:0xf
	v_fmac_f32_dpp v15, v19, v27 quad_perm:[1,0,3,2] row_mask:0xf bank_mask:0xf
	global_store_dword v7, v12, s[40:41] offset:0
	global_store_dword v7, v13, s[40:41] offset:128
	global_store_dword v7, v14, s[40:41] offset:256
	global_store_dword v7, v15, s[40:41] offset:384
	s_cmpk_gt_u32 s5, 0x83f
	s_cbranch_scc0 .Lp6_top
.Lp6_done:
.LBB0_536:
	s_cmp_gt_i32 s91, 7
	s_cselect_b64 s[2:3], -1, 0
	s_and_b64 s[0:1], s[0:1], s[2:3]
	s_andn2_b64 vcc, exec, s[0:1]
	s_cbranch_vccnz .LBB0_590
	s_waitcnt vmcnt(0)
	s_waitcnt lgkmcnt(0)
	s_barrier
	s_and_saveexec_b64 s[0:1], s[92:93]
	s_cbranch_execz .LBB0_589
	s_add_i32 s4, 0, 0x27ff0
	v_mov_b32_e32 v0, s4
	s_waitcnt vmcnt(0) expcnt(0) lgkmcnt(0)
	ds_read_b32 v2, v0
	s_add_i32 s4, 0, 0x27ff4
	v_mov_b32_e32 v0, s4
	ds_read_b32 v0, v0
	s_waitcnt lgkmcnt(1)
	v_cmp_ne_u32_e32 vcc, 0, v2
	s_cbranch_vccnz .LBB0_553
	s_add_u32 s4, s30, 0x38200
	s_addc_u32 s5, s31, 0
	s_add_u32 s6, s30, 0x38400
	s_addc_u32 s7, s31, 0
	s_add_u32 s10, s30, 0x38500
	s_addc_u32 s11, s31, 0
	s_add_u32 s12, s30, 0x38600
	s_addc_u32 s13, s31, 0
	s_add_u32 s14, s30, 0x38700
	s_addc_u32 s15, s31, 0
	s_add_u32 s16, s30, 0x38800
	s_addc_u32 s17, s31, 0
	s_add_u32 s18, s30, 0x38900
	s_addc_u32 s19, s31, 0
	s_add_u32 s20, s30, 0x38a00
	s_addc_u32 s21, s31, 0
	s_add_u32 s22, s30, 0x38b00
	s_addc_u32 s23, s31, 0
	s_add_u32 s24, s30, 0x38c00
	s_addc_u32 s25, s31, 0
	s_add_u32 s26, s30, 0x38d00
	s_addc_u32 s27, s31, 0
	s_add_u32 s34, s30, 0x38e00
	s_addc_u32 s35, s31, 0
	s_add_u32 s40, s30, 0x38f00
	s_addc_u32 s41, s31, 0
	s_add_u32 s44, s30, 0x39000
	s_addc_u32 s45, s31, 0
	s_add_u32 s46, s30, 0x39100
	s_addc_u32 s47, s31, 0
	s_add_u32 s48, s30, 0x39200
	s_addc_u32 s49, s31, 0
	s_mul_i32 s33, s89, s9
	s_add_u32 s54, s30, 0x39300
	s_mul_i32 s33, s33, s88
	s_addc_u32 s55, s31, 0
	s_mov_b32 s62, 1
	v_mov_b32_e32 v16, 0
	s_branch .LBB0_541
